# after all chains are done every WG runs one P7 output group before each next attention unit (P7 drained before the light attention tail)
# speedup vs baseline: 1.0019x; 1.0019x over previous
.LBB0_1084:
	ds_read_b32 v2, v209
	ds_read_b32 v253, v209 offset:8
	s_mov_b64 s[22:23], -1
	s_waitcnt lgkmcnt(0)
	s_barrier
	v_cmp_lt_i32_e32 vcc, s79, v2
	v_readfirstlane_b32 s50, v2
	s_cbranch_vccnz .LBB0_1083
	v_readfirstlane_b32 s98, v253
	s_nop 0
	s_cmp_lg_u32 s98, 0
	s_cbranch_scc0 .Latt_cont
	s_branch .Lp7_mid
